# LDS bank conflicts: SWA transposed-V row stride 528->544 B so the swizzled P.V operand reads are conflict-free
# speedup vs baseline: 1.0186x; 1.0010x over previous
.LBB0_423:
	v_readlane_b32 s14, v254, 9
	v_readlane_b32 s15, v254, 10
	s_mov_b64 s[12:13], s[84:85]
	v_mov_b32_e32 v0, v208
	s_mov_b64 s[6:7], s[84:85]
	s_mov_b64 s[8:9], s[84:85]
	s_mov_b64 s[10:11], s[84:85]
	s_and_b64 vcc, exec, s[14:15]
	s_cbranch_vccz .Lswap_swa_exit
	s_load_dwordx2 s[86:87], s[12:13], 0x80
	s_lshl_b32 s94, s36, 3
	s_load_dwordx2 s[12:13], s[10:11], 0x40
	s_load_dwordx2 s[14:15], s[6:7], 0x30
	s_nop 0
	s_load_dwordx2 s[8:9], s[8:9], 0x38
	v_lshlrev_b32_e32 v3, 5, v0
	s_waitcnt lgkmcnt(0)
	s_add_u32 s10, s86, 0xbe00000
	s_addc_u32 s11, s87, 0
	s_lshl_b64 s[6:7], s[94:95], 2
	s_add_u32 s6, s12, s6
	s_addc_u32 s7, s13, s7
	s_lshl_b32 s94, s36, 6
	s_lshl_b64 s[12:13], s[94:95], 2
	s_waitcnt vmcnt(11)
	v_and_b32_e32 v5, 64, v211
	s_add_u32 s8, s8, s12
	v_and_b32_e32 v6, 32, v3
	v_xor_b32_e32 v3, 1, v211
	v_add_u32_e32 v5, 64, v5
	s_addc_u32 s9, s9, s13
	v_cmp_lt_i32_e32 vcc, v3, v5
	s_waitcnt vmcnt(10)
	v_lshlrev_b32_e32 v8, 2, v6
	v_mov_b32_e32 v9, v2
	v_ashrrev_i32_e32 v136, 1, v0
	v_cndmask_b32_e32 v3, v211, v3, vcc
	v_lshl_add_u64 v[116:117], s[8:9], 0, v[8:9]
	s_movk_i32 s8, 0x90
	v_lshlrev_b32_e32 v138, 2, v3
	v_mul_lo_u32 v3, v136, s8
	v_lshlrev_b32_e32 v7, 1, v6
	v_add3_u32 v139, 0, v3, v7
	v_xor_b32_e32 v7, 16, v211
	v_cmp_lt_i32_e32 vcc, v7, v5
	v_ashrrev_i32_e32 v1, 6, v0
	v_and_b32_e32 v112, 15, v0
	v_cndmask_b32_e32 v7, v211, v7, vcc
	v_lshlrev_b32_e32 v141, 2, v7
	v_xor_b32_e32 v7, 32, v211
	v_lshlrev_b32_e32 v114, 4, v1
	v_cmp_lt_i32_e32 vcc, v7, v5
	v_bfe_u32 v113, v0, 4, 2
	s_add_u32 s12, s14, s12
	v_cndmask_b32_e32 v5, v211, v7, vcc
	v_or_b32_e32 v7, v114, v112
	v_mul_lo_u32 v144, v7, s8
	v_cmp_lt_i32_e64 s[8:9], 7, v1
	v_lshlrev_b32_e32 v0, 4, v0
	s_addc_u32 s13, s15, s13
	v_writelane_b32 v253, s8, 11
	v_and_b32_e32 v137, -2, v136
	v_and_b32_e32 v0, 48, v0
	v_writelane_b32 v253, s9, 12
	v_cmp_lt_i32_e64 s[8:9], 6, v1
	v_lshlrev_b32_e32 v8, 5, v113
	v_lshlrev_b32_e32 v4, 3, v113
	v_writelane_b32 v253, s8, 13
	v_lshl_add_u32 v3, v137, 1, 0
	v_lshl_add_u64 v[118:119], s[12:13], 0, v[8:9]
	v_writelane_b32 v253, s9, 14
	v_cmp_lt_i32_e64 s[8:9], 5, v1
	v_lshl_add_u32 v140, v113, 4, 0
	v_lshlrev_b32_e32 v142, 2, v5
	v_writelane_b32 v253, s8, 15
	v_mul_u32_u24_e32 v5, 0x220, v0
	v_add_u32_e32 v7, 0x900, v144
	v_writelane_b32 v253, s9, 16
	v_cmp_lt_i32_e64 s[8:9], 4, v1
	v_add_u32_e32 v8, 0x1200, v144
	v_add_u32_e32 v9, 0x1b00, v144
	v_writelane_b32 v253, s8, 17
	v_add_u32_e32 v10, 0x2400, v144
	v_add_u32_e32 v11, 0x2d00, v144
	v_writelane_b32 v253, s9, 18
	v_cmp_lt_i32_e64 s[8:9], 3, v1
	s_waitcnt vmcnt(9)
	v_add_u32_e32 v12, 0x3600, v144
	v_add_u32_e32 v13, 0x3f00, v144
	v_writelane_b32 v253, s8, 19
	v_add_u32_e32 v14, 0x4800, v144
	v_readlane_b32 s92, v254, 45
	v_writelane_b32 v253, s9, 20
	v_cmp_lt_i32_e64 s[8:9], 2, v1
	v_ashrrev_i32_e32 v115, 31, v114
	v_lshl_add_u32 v143, v1, 5, 0
	v_writelane_b32 v253, s8, 21
	v_lshlrev_b32_e32 v120, 1, v4
	v_lshlrev_b32_e32 v122, 1, v6
	v_writelane_b32 v253, s9, 22
	v_cmp_lt_i32_e64 s[8:9], 1, v1
	v_lshlrev_b32_e32 v124, 1, v0
	v_add_u32_e32 v145, v3, v5
	v_writelane_b32 v253, s8, 23
	v_add_u32_e32 v146, v140, v7
	v_add_u32_e32 v147, v140, v8
	v_writelane_b32 v253, s9, 24
	v_cmp_lt_i32_e64 s[8:9], 0, v1
	v_add_u32_e32 v148, v140, v9
	v_add_u32_e32 v149, v140, v10
	v_writelane_b32 v253, s8, 25
	v_add_u32_e32 v150, v140, v11
	v_add_u32_e32 v151, v140, v12
	v_writelane_b32 v253, s9, 26
	v_cmp_lt_i32_e64 s[8:9], -1, v1
	v_add_u32_e32 v152, v140, v13
	v_add_u32_e32 v153, v140, v14
	v_writelane_b32 v253, s8, 27
	v_readlane_b32 s93, v254, 46
	s_nop 0
	v_writelane_b32 v253, s9, 28
	s_mov_b32 s8, s78
	s_branch .LBB0_426

.LBB0_426:
	v_cndmask_b32_e64 v3, 0, 1, s[92:93]
	v_mov_b64_e32 v[0:1], s[10:11]
	v_readfirstlane_b32 s12, v3
	s_lshl_b32 s9, s12, 2
	s_or_b32 s9, s9, 2
	s_lshl_b32 s12, s12, 9
	s_add_u32 s12, s86, s12
	s_addc_u32 s13, s87, 0
	s_ashr_i32 s26, s8, 7
	s_bfe_u32 s24, s8, 0x60001
	s_ashr_i32 s27, s26, 31
	s_lshl_b64 s[28:29], s[26:27], 13
	s_lshl_b32 s14, s24, 7
	s_or_b32 s28, s28, s14
	s_lshl_b32 s25, s26, 13
	v_lshl_add_u64 v[126:127], s[28:29], 0, v[114:115]
	s_or_b32 s14, s25, s14
	v_or_b32_e32 v4, v126, v112
	s_addk_i32 s14, 0xff80
	s_and_b32 s15, s8, 1
	v_mad_u64_u32 v[4:5], s[28:29], v4, s62, v[0:1]
	v_add_u32_e32 v6, s14, v136
	v_mad_i32_i24 v5, v127, s62, v5
	s_lshl_b32 s94, s15, 9
	v_max_i32_e32 v6, s25, v6
	v_lshl_add_u64 v[4:5], v[4:5], 0, s[94:95]
	v_mad_i64_i32 v[6:7], s[26:27], v6, s62, v[0:1]
	s_lshl_b32 s94, s15, 7
	v_lshl_add_u64 v[6:7], v[6:7], 0, s[94:95]
	v_mov_b32_e32 v123, v2
	v_lshl_add_u64 v[6:7], v[6:7], 0, v[122:123]
	s_mov_b64 s[26:27], 0x1000
	v_lshl_add_u64 v[8:9], v[6:7], 0, s[26:27]
	global_load_dwordx4 v[12:15], v[8:9], off offset:16
	global_load_dwordx4 v[16:19], v[8:9], off offset:32
	s_movk_i32 s28, 0x1000
	v_add_co_u32_e32 v6, vcc, s28, v6
	v_mov_b32_e32 v121, v2
	s_nop 0
	v_addc_co_u32_e32 v7, vcc, 0, v7, vcc
	global_load_dwordx4 v[20:23], v[6:7], off
	global_load_dwordx4 v[24:27], v[116:117], off offset:16
	global_load_dwordx4 v[28:31], v[116:117], off
	global_load_dwordx4 v[32:35], v[8:9], off offset:48
	v_add_u32_e32 v6, s14, v137
	v_max_i32_e32 v10, s25, v6
	v_mad_i64_i32 v[6:7], s[26:27], v10, s62, v[0:1]
	v_mov_b32_e32 v125, v2
	v_or_b32_e32 v10, 1, v10
	v_lshl_add_u64 v[4:5], v[4:5], 0, v[120:121]
	v_lshl_add_u64 v[6:7], v[6:7], 0, s[94:95]
	v_mad_i64_i32 v[0:1], s[26:27], v10, s62, v[0:1]
	global_load_dwordx4 v[96:99], v[4:5], off offset:3072
	global_load_dwordx4 v[100:103], v[4:5], off offset:3136
	v_lshl_add_u64 v[4:5], v[6:7], 0, v[124:125]
	s_mov_b64 s[16:17], 0x1100
	v_lshl_add_u64 v[0:1], v[0:1], 0, s[94:95]
	v_lshl_add_u64 v[48:49], v[4:5], 0, s[16:17]
	v_add_co_u32_e32 v4, vcc, s28, v4
	v_lshl_add_u64 v[0:1], v[0:1], 0, v[124:125]
	s_nop 0
	v_addc_co_u32_e32 v5, vcc, 0, v5, vcc
	v_lshl_add_u64 v[50:51], v[0:1], 0, s[16:17]
	v_add_co_u32_e32 v0, vcc, s28, v0
	s_mov_b32 s14, 0xffff0000
	s_nop 0
	v_addc_co_u32_e32 v1, vcc, 0, v1, vcc
	global_load_dwordx4 v[4:7], v[4:5], off offset:256
	s_nop 0
	global_load_dwordx4 v[8:11], v[0:1], off offset:256
	v_readlane_b32 s16, v253, 11
	v_readlane_b32 s17, v253, 12
	v_mov_b32_e32 v129, v2
	s_mov_b64 s[70:71], 0
	s_movk_i32 s94, 0x220
	s_mov_b32 s18, 0x41800000
	s_mov_b32 s19, 0x41880000
	s_mov_b32 s20, 0x41900000
	s_mov_b32 s21, 0x41980000
	s_mov_b32 s22, 0x42000000
	s_waitcnt vmcnt(9)
	v_and_b32_e32 v53, 0xffff0000, v13
	v_and_b32_e32 v52, 0xffff0000, v12
	v_and_b32_e32 v57, 0xffff0000, v15
	v_and_b32_e32 v56, 0xffff0000, v14
	v_lshlrev_b32_e32 v1, 16, v13
	v_lshlrev_b32_e32 v0, 16, v12
	v_lshlrev_b32_e32 v55, 16, v15
	v_lshlrev_b32_e32 v54, 16, v14
	s_waitcnt vmcnt(8)
	v_and_b32_e32 v59, 0xffff0000, v16
	v_and_b32_e32 v61, 0xffff0000, v17
	v_pk_mul_f32 v[12:13], v[52:53], v[52:53]
	v_pk_mul_f32 v[14:15], v[56:57], v[56:57]
	v_lshlrev_b32_e32 v58, 16, v16
	v_lshlrev_b32_e32 v60, 16, v17
	v_lshlrev_b32_e32 v62, 16, v18
	v_and_b32_e32 v63, 0xffff0000, v18
	v_mul_f32_e32 v16, v59, v59
	v_mul_f32_e32 v18, v61, v61
	v_pk_fma_f32 v[12:13], v[0:1], v[0:1], v[12:13]
	v_pk_fma_f32 v[14:15], v[54:55], v[54:55], v[14:15]
	v_lshlrev_b32_e32 v64, 16, v19
	v_and_b32_e32 v65, 0xffff0000, v19
	v_pk_fma_f32 v[66:67], v[58:59], v[58:59], v[16:17] op_sel_hi:[1,1,0]
	v_pk_fma_f32 v[68:69], v[60:61], v[60:61], v[18:19] op_sel_hi:[1,1,0]
	v_pk_add_f32 v[72:73], v[12:13], v[12:13] op_sel:[0,1] op_sel_hi:[1,0]
	v_pk_add_f32 v[74:75], v[14:15], v[14:15] op_sel:[0,1] op_sel_hi:[1,0]
	global_load_dwordx4 v[12:15], v[116:117], off offset:48
	global_load_dwordx4 v[16:19], v[116:117], off offset:32
	v_mul_f32_e32 v36, v63, v63
	s_waitcnt vmcnt(9)
	v_and_b32_e32 v79, 0xffff0000, v23
	v_and_b32_e32 v81, 0xffff0000, v22
	v_pk_fma_f32 v[70:71], v[62:63], v[62:63], v[36:37] op_sel_hi:[1,1,0]
	v_lshlrev_b32_e32 v78, 16, v23
	v_lshlrev_b32_e32 v80, 16, v22
	v_mov_b32_e32 v36, v81
	v_mov_b32_e32 v37, v79
	v_mov_b32_e32 v22, v80
	v_mov_b32_e32 v23, v78
	v_pk_mul_f32 v[36:37], v[36:37], v[36:37]
	v_mul_f32_e32 v38, v65, v65
	v_pk_fma_f32 v[22:23], v[22:23], v[22:23], v[36:37]
	v_pk_fma_f32 v[76:77], v[64:65], v[64:65], v[38:39] op_sel_hi:[1,1,0]
	v_pk_add_f32 v[82:83], v[22:23], v[22:23] op_sel:[0,1] op_sel_hi:[1,0]
	v_lshlrev_b32_e32 v84, 16, v21
	v_and_b32_e32 v85, 0xffff0000, v21
	v_lshlrev_b32_e32 v86, 16, v20
	v_and_b32_e32 v87, 0xffff0000, v20
	global_load_dwordx4 v[20:23], v[116:117], off offset:80
	global_load_dwordx4 v[36:39], v[116:117], off offset:64
	v_mov_b32_e32 v42, v87
	v_mov_b32_e32 v43, v85
	v_mov_b32_e32 v40, v86
	v_mov_b32_e32 v41, v84
	v_pk_mul_f32 v[42:43], v[42:43], v[42:43]
	s_waitcnt vmcnt(8)
	v_lshlrev_b32_e32 v90, 16, v35
	v_pk_fma_f32 v[40:41], v[40:41], v[40:41], v[42:43]
	v_and_b32_e32 v91, 0xffff0000, v35
	v_pk_add_f32 v[88:89], v[40:41], v[40:41] op_sel:[0,1] op_sel_hi:[1,0]
	global_load_dwordx4 v[40:43], v[116:117], off offset:112
	global_load_dwordx4 v[44:47], v[116:117], off offset:96
	v_pk_mul_f32 v[92:93], v[90:91], v[90:91]
	s_nop 0
	v_mov_b32_e32 v71, v92
	v_mov_b32_e32 v77, v93
	v_pk_add_f32 v[70:71], v[70:71], v[76:77]
	v_lshlrev_b32_e32 v76, 16, v34
	v_and_b32_e32 v77, 0xffff0000, v34
	v_pk_mul_f32 v[34:35], v[76:77], v[76:77]
	s_nop 0
	v_mov_b32_e32 v67, v34
	v_mov_b32_e32 v69, v35
	v_pk_add_f32 v[34:35], v[66:67], v[68:69]
	v_lshlrev_b32_e32 v66, 16, v33
	v_pk_add_f32 v[34:35], v[34:35], v[70:71]
	v_and_b32_e32 v67, 0xffff0000, v33
	v_lshlrev_b32_e32 v70, 16, v32
	v_and_b32_e32 v71, 0xffff0000, v32
	v_pk_mul_f32 v[68:69], v[66:67], v[66:67]
	v_pk_mul_f32 v[32:33], v[70:71], v[70:71]
	v_mov_b32_e32 v73, v68
	v_mov_b32_e32 v75, v69
	v_mov_b32_e32 v89, v32
	v_mov_b32_e32 v83, v33
	v_pk_add_f32 v[68:69], v[72:73], v[74:75]
	v_pk_add_f32 v[32:33], v[88:89], v[82:83]
	s_nop 0
	v_pk_add_f32 v[32:33], v[32:33], v[68:69]
	v_mov_b32_e32 v68, v0
	v_pk_add_f32 v[32:33], v[32:33], v[34:35]
	v_mov_b32_e32 v69, v52
	v_add_f32_e32 v72, v32, v33
	global_load_dwordx4 v[32:35], v[48:49], off offset:16
	s_nop 0
	global_load_dwordx4 v[48:51], v[50:51], off offset:16
	ds_bpermute_b32 v73, v138, v72
	v_mov_b32_e32 v52, v1
	s_waitcnt lgkmcnt(0)
	v_add_f32_e32 v0, v72, v73
	v_fmamk_f32 v0, v0, 0x3c800000, v209
	v_mul_f32_e32 v1, 0x4b800000, v0
	v_cmp_gt_f32_e32 vcc, s68, v0
	s_nop 1
	v_cndmask_b32_e32 v0, v0, v1, vcc
	v_rsq_f32_e32 v72, v0
	v_mov_b32_e32 v0, v54
	v_mov_b32_e32 v1, v56
	v_mov_b32_e32 v56, v55
	v_mul_f32_e32 v54, 0x45800000, v72
	v_cndmask_b32_e32 v54, v72, v54, vcc
	v_pk_mul_f32 v[72:73], v[54:55], v[86:87] op_sel_hi:[0,1]
	v_pk_mul_f32 v[28:29], v[28:29], v[72:73]
	v_pk_mul_f32 v[72:73], v[54:55], v[84:85] op_sel_hi:[0,1]
	v_pk_mul_f32 v[30:31], v[30:31], v[72:73]
	v_cvt_pk_bf16_f32 v28, v28, v29
	v_cvt_pk_bf16_f32 v29, v30, v31
	v_pk_mul_f32 v[30:31], v[54:55], v[80:81] op_sel_hi:[0,1]
	v_pk_mul_f32 v[24:25], v[24:25], v[30:31]
	v_pk_mul_f32 v[0:1], v[54:55], v[0:1] op_sel_hi:[0,1]
	v_cvt_pk_bf16_f32 v30, v24, v25
	v_pk_mul_f32 v[24:25], v[54:55], v[78:79] op_sel_hi:[0,1]
	v_pk_mul_f32 v[24:25], v[26:27], v[24:25]
	s_waitcnt vmcnt(7)
	v_pk_mul_f32 v[0:1], v[12:13], v[0:1]
	v_cvt_pk_bf16_f32 v31, v24, v25
	v_pk_mul_f32 v[24:25], v[54:55], v[68:69] op_sel_hi:[0,1]
	s_waitcnt vmcnt(6)
	v_pk_mul_f32 v[16:17], v[16:17], v[24:25]
	v_pk_mul_f32 v[24:25], v[54:55], v[52:53] op_sel_hi:[0,1]
	v_pk_mul_f32 v[18:19], v[18:19], v[24:25]
	v_cvt_pk_bf16_f32 v16, v16, v17
	v_cvt_pk_bf16_f32 v17, v18, v19
	v_cvt_pk_bf16_f32 v18, v0, v1
	v_pk_mul_f32 v[0:1], v[54:55], v[56:57] op_sel_hi:[0,1]
	v_pk_mul_f32 v[0:1], v[14:15], v[0:1]
	ds_write_b128 v139, v[28:31]
	v_cvt_pk_bf16_f32 v19, v0, v1
	v_pk_mul_f32 v[0:1], v[54:55], v[58:59] op_sel_hi:[0,1]
	s_waitcnt vmcnt(4)
	v_pk_mul_f32 v[0:1], v[36:37], v[0:1]
	ds_write_b128 v139, v[16:19] offset:16
	v_cvt_pk_bf16_f32 v12, v0, v1
	v_pk_mul_f32 v[0:1], v[54:55], v[60:61] op_sel_hi:[0,1]
	v_pk_mul_f32 v[0:1], v[38:39], v[0:1]
	s_nop 0
	v_cvt_pk_bf16_f32 v13, v0, v1
	v_pk_mul_f32 v[0:1], v[54:55], v[62:63] op_sel_hi:[0,1]
	v_pk_mul_f32 v[0:1], v[20:21], v[0:1]
	s_nop 0
	v_cvt_pk_bf16_f32 v14, v0, v1
	v_pk_mul_f32 v[0:1], v[54:55], v[64:65] op_sel_hi:[0,1]
	v_pk_mul_f32 v[0:1], v[22:23], v[0:1]
	s_nop 0
	v_cvt_pk_bf16_f32 v15, v0, v1
	v_pk_mul_f32 v[0:1], v[54:55], v[70:71] op_sel_hi:[0,1]
	s_waitcnt vmcnt(2)
	v_pk_mul_f32 v[0:1], v[44:45], v[0:1]
	ds_write_b128 v139, v[12:15] offset:32
	v_cvt_pk_bf16_f32 v12, v0, v1
	v_pk_mul_f32 v[0:1], v[54:55], v[66:67] op_sel_hi:[0,1]
	v_pk_mul_f32 v[0:1], v[46:47], v[0:1]
	s_nop 0
	v_cvt_pk_bf16_f32 v13, v0, v1
	v_pk_mul_f32 v[0:1], v[54:55], v[76:77] op_sel_hi:[0,1]
	v_pk_mul_f32 v[0:1], v[40:41], v[0:1]
	s_nop 0
	v_cvt_pk_bf16_f32 v14, v0, v1
	v_pk_mul_f32 v[0:1], v[54:55], v[90:91] op_sel_hi:[0,1]
	v_pk_mul_f32 v[0:1], v[42:43], v[0:1]
	s_nop 0
	v_cvt_pk_bf16_f32 v15, v0, v1
	v_and_b32_e32 v0, 0xffff, v4
	v_lshrrev_b32_e32 v1, 16, v4
	v_lshl_or_b32 v0, v8, 16, v0
	v_and_or_b32 v1, v8, s14, v1
	v_and_b32_e32 v28, 1, v208
	v_lshlrev_b32_e32 v28, 4, v28
	v_xor_b32_e32 v28, v145, v28
	v_xor_b32_e32 v29, 8, v28
	v_add_u32_e32 v4, 0x9000, v28
	ds_write_b128 v139, v[12:15] offset:48
	ds_write2_b32 v4, v0, v1 offset1:136
	v_and_b32_e32 v0, 0xffff, v5
	v_lshrrev_b32_e32 v1, 16, v5
	v_lshl_or_b32 v0, v9, 16, v0
	v_and_or_b32 v1, v9, s14, v1
	v_add_u32_e32 v4, 0x9400, v28
	ds_write2_b32 v4, v0, v1 offset0:16 offset1:152
	v_and_b32_e32 v0, 0xffff, v6
	v_lshrrev_b32_e32 v1, 16, v6
	v_lshl_or_b32 v0, v10, 16, v0
	v_and_or_b32 v1, v10, s14, v1
	v_add_u32_e32 v4, 0x9800, v28
	ds_write2_b32 v4, v0, v1 offset0:32 offset1:168
	v_and_b32_e32 v0, 0xffff, v7
	v_lshrrev_b32_e32 v1, 16, v7
	v_lshl_or_b32 v0, v11, 16, v0
	v_and_or_b32 v1, v11, s14, v1
	v_add_u32_e32 v4, 0x9c00, v28
	ds_write2_b32 v4, v0, v1 offset0:48 offset1:184
	s_waitcnt vmcnt(1)
	v_and_b32_e32 v0, 0xffff, v32
	v_lshrrev_b32_e32 v1, 16, v32
	s_waitcnt vmcnt(0)
	v_lshl_or_b32 v0, v48, 16, v0
	v_and_or_b32 v1, v48, s14, v1
	v_add_u32_e32 v4, 0xa000, v29
	ds_write2_b32 v4, v0, v1 offset0:64 offset1:200
	v_and_b32_e32 v0, 0xffff, v33
	v_lshrrev_b32_e32 v1, 16, v33
	v_lshl_or_b32 v0, v49, 16, v0
	v_and_or_b32 v1, v49, s14, v1
	v_add_u32_e32 v4, 0xa400, v29
	ds_write2_b32 v4, v0, v1 offset0:80 offset1:216
	v_and_b32_e32 v0, 0xffff, v34
	v_lshrrev_b32_e32 v1, 16, v34
	v_lshl_or_b32 v0, v50, 16, v0
	v_and_or_b32 v1, v50, s14, v1
	v_add_u32_e32 v4, 0xa800, v29
	ds_write2_b32 v4, v0, v1 offset0:96 offset1:232
	v_and_b32_e32 v0, 0xffff, v35
	v_lshrrev_b32_e32 v1, 16, v35
	v_lshl_or_b32 v0, v51, 16, v0
	v_and_or_b32 v1, v51, s14, v1
	v_add_u32_e32 v4, 0xac00, v29
	ds_write2_b32 v4, v0, v1 offset0:112 offset1:248
	s_waitcnt lgkmcnt(0)
	s_barrier
	global_load_dwordx4 v[4:7], v[118:119], off
	global_load_dwordx4 v[8:11], v[118:119], off offset:16
	global_load_dwordx4 v[12:15], v[118:119], off offset:128
	global_load_dwordx4 v[16:19], v[118:119], off offset:144
	s_lshl_b32 s14, s15, 4
	v_mov_b32_e32 v0, s14
	global_load_dwordx4 v[20:23], v0, s[6:7]
	v_lshlrev_b32_e32 v0, 8, v3
	v_or_b32_e32 v128, 64, v0
	v_add_u32_e32 v0, v140, v144
	ds_read_b128 v[24:27], v0
	ds_read_b128 v[28:31], v0 offset:64
	ds_read_b128 v[32:35], v146
	ds_read_b128 v[36:39], v146 offset:64
	ds_read_b128 v[40:43], v147
	ds_read_b128 v[44:47], v147 offset:64
	ds_read_b128 v[48:51], v148
	ds_read_b128 v[52:55], v148 offset:64
	ds_read_b128 v[56:59], v149
	ds_read_b128 v[60:63], v149 offset:64
	ds_read_b128 v[64:67], v150
	ds_read_b128 v[68:71], v150 offset:64
	ds_read_b128 v[72:75], v151
	ds_read_b128 v[76:79], v151 offset:64
	ds_read_b128 v[80:83], v152
	ds_read_b128 v[84:87], v152 offset:64
	ds_read_b128 v[88:91], v153
	ds_read_b128 v[92:95], v153 offset:64
	s_lshl_b32 s15, s15, 2
	s_cmp_lg_u32 s24, 0
	s_cselect_b64 s[40:41], -1, 0
	s_or_b64 s[78:79], s[40:41], s[16:17]
	v_readlane_b32 s16, v253, 13
	v_readlane_b32 s17, v253, 14
	s_or_b64 s[24:25], s[40:41], s[16:17]
	v_readlane_b32 s16, v253, 15
	v_readlane_b32 s17, v253, 16
	s_or_b64 s[26:27], s[40:41], s[16:17]
	v_readlane_b32 s16, v253, 17
	v_readlane_b32 s17, v253, 18
	s_or_b64 s[28:29], s[40:41], s[16:17]
	v_readlane_b32 s16, v253, 19
	v_readlane_b32 s17, v253, 20
	s_or_b64 s[30:31], s[40:41], s[16:17]
	v_readlane_b32 s16, v253, 21
	v_readlane_b32 s17, v253, 22
	s_or_b64 s[34:35], s[40:41], s[16:17]
	v_readlane_b32 s16, v253, 23
	v_readlane_b32 s17, v253, 24
	s_or_b64 s[36:37], s[40:41], s[16:17]
	v_readlane_b32 s16, v253, 25
	v_readlane_b32 s17, v253, 26
	s_or_b64 s[38:39], s[40:41], s[16:17]
	v_readlane_b32 s16, v253, 27
	v_readlane_b32 s17, v253, 28
	s_mov_b32 s14, 0
	s_or_b64 s[84:85], s[40:41], s[16:17]
	s_mov_b32 s16, 0x42800000
	s_mov_b32 s17, 0x40400000
	s_branch .LBB0_429

.LBB0_428:
	s_waitcnt vmcnt(3)
	v_lshlrev_b32_e32 v186, 16, v104
	v_and_b32_e32 v187, 0xffff0000, v104
	v_lshlrev_b32_e32 v182, 16, v105
	v_and_b32_e32 v183, 0xffff0000, v105
	v_pk_mul_f32 v[104:105], v[186:187], v[186:187]
	v_pk_mul_f32 v[184:185], v[182:183], v[182:183]
	v_add_f32_e32 v1, v104, v105
	v_lshlrev_b32_e32 v180, 16, v106
	v_and_b32_e32 v181, 0xffff0000, v106
	v_add_f32_e32 v1, v184, v1
	v_lshlrev_b32_e32 v176, 16, v107
	v_and_b32_e32 v177, 0xffff0000, v107
	v_pk_mul_f32 v[106:107], v[180:181], v[180:181]
	v_add_f32_e32 v1, v185, v1
	v_add_f32_e32 v1, v106, v1
	v_pk_mul_f32 v[178:179], v[176:177], v[176:177]
	v_add_f32_e32 v1, v107, v1
	s_waitcnt vmcnt(2)
	v_lshlrev_b32_e32 v174, 16, v108
	v_and_b32_e32 v175, 0xffff0000, v108
	v_add_f32_e32 v1, v178, v1
	v_lshlrev_b32_e32 v170, 16, v109
	v_and_b32_e32 v171, 0xffff0000, v109
	v_pk_mul_f32 v[108:109], v[174:175], v[174:175]
	v_add_f32_e32 v1, v179, v1
	v_add_f32_e32 v1, v108, v1
	v_pk_mul_f32 v[172:173], v[170:171], v[170:171]
	v_add_f32_e32 v1, v109, v1
	v_lshlrev_b32_e32 v160, 16, v110
	v_and_b32_e32 v161, 0xffff0000, v110
	v_add_f32_e32 v1, v172, v1
	v_lshlrev_b32_e32 v154, 16, v111
	v_and_b32_e32 v155, 0xffff0000, v111
	v_pk_mul_f32 v[110:111], v[160:161], v[160:161]
	v_add_f32_e32 v1, v173, v1
	v_add_f32_e32 v1, v110, v1
	v_pk_mul_f32 v[158:159], v[154:155], v[154:155]
	v_add_f32_e32 v1, v111, v1
	v_add_f32_e32 v1, v158, v1
	v_add_f32_e32 v1, v159, v1
	ds_bpermute_b32 v104, v141, v1
	v_lshlrev_b32_e32 v3, 2, v3
	v_sub_u32_e32 v3, v0, v3
	s_mov_b32 s17, 0x40400000
	s_mov_b32 s18, 0x41800000
	s_waitcnt lgkmcnt(0)
	v_add_f32_e32 v1, v1, v104
	ds_bpermute_b32 v104, v142, v1
	s_mov_b32 s19, 0x41880000
	s_mov_b32 s20, 0x41900000
	s_mov_b32 s21, 0x41980000
	s_mov_b32 s22, 0x42000000
	s_waitcnt lgkmcnt(0)
	v_add_f32_e32 v1, v1, v104
	v_fmamk_f32 v1, v1, 0x3c800000, v209
	v_cmp_gt_f32_e32 vcc, s68, v1
	v_mul_f32_e32 v104, 0x4b800000, v1
	s_mov_b32 s16, 0x42800000
	v_cndmask_b32_e32 v1, v1, v104, vcc
	v_rsq_f32_e32 v1, v1
	s_movk_i32 s94, 0x220
	v_lshlrev_b64 v[132:133], 11, v[132:133]
	v_lshl_add_u64 v[132:133], s[86:87], 0, v[132:133]
	v_mul_f32_e32 v104, 0x45800000, v1
	v_cndmask_b32_e32 v1, v1, v104, vcc
	v_mul_f32_e32 v158, 0x3e38aa3b, v1
	v_pk_mul_f32 v[104:105], v[158:159], v[186:187] op_sel_hi:[0,1]
	v_pk_mul_f32 v[106:107], v[158:159], v[182:183] op_sel_hi:[0,1]
	v_pk_mul_f32 v[104:105], v[4:5], v[104:105]
	v_pk_mul_f32 v[106:107], v[6:7], v[106:107]
	v_cvt_pk_bf16_f32 v104, v104, v105
	v_cvt_pk_bf16_f32 v105, v106, v107
	v_pk_mul_f32 v[106:107], v[158:159], v[180:181] op_sel_hi:[0,1]
	v_pk_mul_f32 v[108:109], v[158:159], v[176:177] op_sel_hi:[0,1]
	v_pk_mul_f32 v[106:107], v[8:9], v[106:107]
	v_pk_mul_f32 v[108:109], v[10:11], v[108:109]
	v_cvt_pk_bf16_f32 v106, v106, v107
	v_cvt_pk_bf16_f32 v107, v108, v109
	v_pk_mul_f32 v[108:109], v[158:159], v[174:175] op_sel_hi:[0,1]
	v_pk_mul_f32 v[110:111], v[158:159], v[170:171] op_sel_hi:[0,1]
	v_cvt_f32_u32_e32 v1, s9
	v_pk_mul_f32 v[108:109], v[12:13], v[108:109]
	v_pk_mul_f32 v[110:111], v[14:15], v[110:111]
	v_mfma_f32_16x16x32_bf16 v[170:173], v[24:27], v[104:107], 0
	v_cvt_pk_bf16_f32 v108, v108, v109
	v_cvt_pk_bf16_f32 v109, v110, v111
	v_pk_mul_f32 v[110:111], v[158:159], v[160:161] op_sel_hi:[0,1]
	v_mfma_f32_16x16x32_bf16 v[174:177], v[32:35], v[104:107], 0
	v_mul_f32_e64 v154, v158, v154
	v_mul_f32_e64 v155, v158, v155
	v_pk_mul_f32 v[110:111], v[16:17], v[110:111]
	v_pk_mul_f32 v[154:155], v[18:19], v[154:155]
	v_mfma_f32_16x16x32_bf16 v[178:181], v[40:43], v[104:107], 0
	v_cvt_pk_bf16_f32 v110, v110, v111
	v_cvt_pk_bf16_f32 v111, v154, v155
	v_cmp_lt_f32_e32 vcc, s57, v1
	v_mfma_f32_16x16x32_bf16 v[182:185], v[48:51], v[104:107], 0
	s_and_b64 s[40:41], vcc, exec
	s_cselect_b32 s40, 0xffffffc0, 0
	s_cmp_eq_u32 s42, 1
	v_mfma_f32_16x16x32_bf16 v[186:189], v[56:59], v[104:107], 0
	v_lshl_add_u64 v[132:133], v[134:135], 1, v[132:133]
	v_lshl_add_u64 v[128:129], v[128:129], 0, s[76:77]
	v_mfma_f32_16x16x32_bf16 v[190:193], v[64:67], v[104:107], 0
	v_mfma_f32_16x16x32_bf16 v[194:197], v[72:75], v[104:107], 0
	v_mfma_f32_16x16x32_bf16 v[198:201], v[80:83], v[104:107], 0
	v_mfma_f32_16x16x32_bf16 v[104:107], v[88:91], v[104:107], 0
	v_mfma_f32_16x16x32_bf16 v[170:173], v[28:31], v[108:111], v[170:173]
	v_mfma_f32_16x16x32_bf16 v[174:177], v[36:39], v[108:111], v[174:177]
	v_mfma_f32_16x16x32_bf16 v[178:181], v[44:47], v[108:111], v[178:181]
	v_mfma_f32_16x16x32_bf16 v[182:185], v[52:55], v[108:111], v[182:185]
	v_mfma_f32_16x16x32_bf16 v[186:189], v[60:63], v[108:111], v[186:189]
	v_mfma_f32_16x16x32_bf16 v[190:193], v[68:71], v[108:111], v[190:193]
	v_mfma_f32_16x16x32_bf16 v[194:197], v[76:79], v[108:111], v[194:197]
	v_mfma_f32_16x16x32_bf16 v[198:201], v[84:87], v[108:111], v[198:201]
	v_mfma_f32_16x16x32_bf16 v[104:107], v[92:95], v[108:111], v[104:107]
	v_cndmask_b32_e32 v108, 0, v215, vcc
	v_sub_f32_e32 v1, v108, v1
	v_exp_f32_e32 v1, v1
	s_cselect_b64 vcc, -1, 0
	v_add_u32_e32 v110, 0x80, v3
	v_cvt_f32_i32_e32 v157, v110
	v_ldexp_f32 v109, v1, s40
	v_cndmask_b32_e32 v1, v23, v21, vcc
	v_cmp_gt_i32_e32 vcc, 0, v3
	s_and_b64 s[46:47], s[78:79], vcc
	v_cmp_gt_i32_e32 vcc, 1, v3
	s_and_b64 s[48:49], s[78:79], vcc
	v_cmp_gt_i32_e32 vcc, 2, v3
	s_and_b64 s[50:51], s[78:79], vcc
	v_cmp_gt_i32_e32 vcc, 3, v3
	s_and_b64 s[52:53], s[78:79], vcc
	v_cmp_lt_i32_e32 vcc, -1, v3
	v_mul_f32_e32 v108, 0x3fb8aa3b, v109
	s_and_b64 s[44:45], s[84:85], vcc
	v_cmp_lt_i32_e32 vcc, 0, v3
	s_and_b64 s[42:43], s[84:85], vcc
	v_cmp_lt_i32_e32 vcc, 1, v3
	v_pk_mul_f32 v[110:111], v[108:109], v[156:157] op_sel_hi:[0,1]
	s_and_b64 s[40:41], s[84:85], vcc
	v_cmp_lt_i32_e32 vcc, 2, v3
	v_fma_f32 v3, v108, 0, -v111
	v_fma_f32 v109, v109, s65, -v111
	v_add_f32_e32 v3, v3, v170
	v_add_f32_e32 v109, v109, v171
	v_fma_f32 v123, v108, 2.0, -v111
	v_fma_f32 v125, v108, s17, -v111
	v_mul_f32_e32 v121, 0x3fb8aa3b, v1
	v_cndmask_b32_e64 v3, v216, v3, s[46:47]
	v_cndmask_b32_e64 v109, v216, v109, s[48:49]
	v_add_f32_e32 v123, v123, v172
	v_add_f32_e32 v125, v125, v173
	v_fma_f32 v154, v108, s18, -v111
	v_fma_f32 v155, v108, s19, -v111
	v_max3_f32 v121, v121, v3, v109
	v_cndmask_b32_e64 v123, v216, v123, s[50:51]
	v_cndmask_b32_e64 v125, v216, v125, s[52:53]
	v_add_f32_e32 v154, v154, v174
	v_add_f32_e32 v155, v155, v175
	v_fma_f32 v157, v108, s20, -v111
	v_fma_f32 v158, v108, s21, -v111
	v_max3_f32 v121, v121, v123, v125
	v_cndmask_b32_e64 v154, v216, v154, s[24:25]
	v_cndmask_b32_e64 v155, v216, v155, s[24:25]
	v_add_f32_e32 v157, v157, v176
	v_add_f32_e32 v158, v158, v177
	v_fma_f32 v159, v108, s22, -v111
	v_fma_f32 v160, v108, s0, -v111
	v_max3_f32 v121, v121, v154, v155
	v_cndmask_b32_e64 v157, v216, v157, s[24:25]
	v_cndmask_b32_e64 v158, v216, v158, s[24:25]
	v_add_f32_e32 v159, v159, v178
	v_add_f32_e32 v160, v160, v179
	v_fma_f32 v161, v108, s33, -v111
	v_fma_f32 v170, v108, s61, -v111
	v_max3_f32 v121, v121, v157, v158
	v_cndmask_b32_e64 v159, v216, v159, s[26:27]
	v_cndmask_b32_e64 v160, v216, v160, s[26:27]
	v_add_f32_e32 v161, v161, v180
	v_add_f32_e32 v170, v170, v181
	v_fma_f32 v171, v108, s4, -v111
	v_fma_f32 v172, v108, s81, -v111
	v_max3_f32 v121, v121, v159, v160
	v_cndmask_b32_e64 v161, v216, v161, s[26:27]
	v_cndmask_b32_e64 v170, v216, v170, s[26:27]
	v_add_f32_e32 v171, v171, v182
	v_add_f32_e32 v172, v172, v183
	v_fma_f32 v173, v108, s69, -v111
	v_fma_f32 v174, v108, s59, -v111
	v_max3_f32 v121, v121, v161, v170
	v_cndmask_b32_e64 v171, v216, v171, s[28:29]
	v_cndmask_b32_e64 v172, v216, v172, s[28:29]
	v_add_f32_e32 v173, v173, v184
	v_add_f32_e32 v174, v174, v185
	v_fma_f32 v175, v108, s16, -v111
	v_fma_f32 v176, v108, s58, -v111
	v_max3_f32 v121, v121, v171, v172
	v_cndmask_b32_e64 v173, v216, v173, s[28:29]
	v_cndmask_b32_e64 v174, v216, v174, s[28:29]
	v_add_f32_e32 v175, v175, v186
	v_add_f32_e32 v176, v176, v187
	v_fma_f32 v177, v108, s64, -v111
	v_fma_f32 v178, v108, s3, -v111
	v_max3_f32 v121, v121, v173, v174
	v_cndmask_b32_e64 v175, v216, v175, s[30:31]
	v_cndmask_b32_e64 v176, v216, v176, s[30:31]
	v_add_f32_e32 v177, v177, v188
	v_add_f32_e32 v178, v178, v189
	v_fma_f32 v179, v108, s2, -v111
	v_fma_f32 v180, v108, s63, -v111
	v_max3_f32 v121, v121, v175, v176
	v_cndmask_b32_e64 v177, v216, v177, s[30:31]
	v_cndmask_b32_e64 v178, v216, v178, s[30:31]
	v_add_f32_e32 v179, v179, v190
	v_add_f32_e32 v180, v180, v191
	v_fma_f32 v181, v108, s82, -v111
	v_fma_f32 v182, v108, s83, -v111
	v_max3_f32 v121, v121, v177, v178
	v_cndmask_b32_e64 v179, v216, v179, s[34:35]
	v_cndmask_b32_e64 v180, v216, v180, s[34:35]
	v_add_f32_e32 v181, v181, v192
	v_add_f32_e32 v182, v182, v193
	v_fma_f32 v183, v108, s80, -v111
	v_fma_f32 v184, v108, s90, -v111
	v_max3_f32 v121, v121, v179, v180
	v_cndmask_b32_e64 v181, v216, v181, s[34:35]
	v_cndmask_b32_e64 v182, v216, v182, s[34:35]
	v_add_f32_e32 v183, v183, v194
	v_add_f32_e32 v184, v184, v195
	v_fma_f32 v185, v108, s91, -v111
	v_fma_f32 v186, v108, s88, -v111
	v_max3_f32 v121, v121, v181, v182
	v_cndmask_b32_e64 v183, v216, v183, s[36:37]
	v_cndmask_b32_e64 v184, v216, v184, s[36:37]
	v_add_f32_e32 v185, v185, v196
	v_add_f32_e32 v186, v186, v197
	v_fma_f32 v187, v108, s89, -v111
	v_fma_f32 v188, v108, s75, -v111
	v_max3_f32 v121, v121, v183, v184
	v_cndmask_b32_e64 v185, v216, v185, s[36:37]
	v_cndmask_b32_e64 v186, v216, v186, s[36:37]
	v_add_f32_e32 v187, v187, v198
	v_add_f32_e32 v188, v188, v199
	v_fma_f32 v189, v108, s96, -v111
	v_fma_f32 v190, v108, s97, -v111
	v_fma_f32 v191, v108, s5, -v111
	v_max3_f32 v121, v121, v185, v186
	v_cndmask_b32_e64 v187, v216, v187, s[38:39]
	v_cndmask_b32_e64 v188, v216, v188, s[38:39]
	v_add_f32_e32 v189, v189, v200
	v_add_f32_e32 v190, v190, v201
	v_add_f32_e32 v104, v191, v104
	v_fma_f32 v191, v108, s60, -v111
	v_fma_f32 v108, v108, s66, -v111
	v_max3_f32 v121, v121, v187, v188
	v_cndmask_b32_e64 v189, v216, v189, s[38:39]
	v_cndmask_b32_e64 v190, v216, v190, s[38:39]
	v_add_f32_e32 v105, v191, v105
	v_add_f32_e32 v106, v108, v106
	v_sub_f32_e32 v108, v110, v111
	s_and_b64 vcc, s[84:85], vcc
	v_max3_f32 v121, v121, v189, v190
	v_cndmask_b32_e64 v104, v216, v104, s[44:45]
	v_cndmask_b32_e64 v105, v216, v105, s[42:43]
	v_add_f32_e32 v107, v108, v107
	v_max3_f32 v121, v121, v104, v105
	v_cndmask_b32_e64 v106, v216, v106, s[40:41]
	v_cndmask_b32_e32 v107, v216, v107, vcc
	v_max3_f32 v108, v121, v106, v107
	ds_bpermute_b32 v110, v141, v108
	s_add_i32 s14, s14, 2
	s_add_u32 s70, s70, 0x100
	s_addc_u32 s71, s71, 0
	s_add_i32 s9, s9, 2
	s_waitcnt lgkmcnt(0)
	v_max_f32_e32 v110, v110, v110
	v_max_f32_e32 v108, v108, v110
	ds_bpermute_b32 v110, v142, v108
	s_cmp_eq_u32 s14, 4
	s_waitcnt lgkmcnt(0)
	v_max_f32_e32 v110, v110, v110
	v_max_f32_e32 v108, v108, v110
	v_sub_f32_e32 v3, v3, v108
	v_exp_f32_e32 v110, v3
	v_sub_f32_e32 v109, v109, v108
	v_exp_f32_e32 v109, v109
	v_sub_f32_e32 v111, v123, v108
	v_exp_f32_e32 v111, v111
	v_sub_f32_e32 v121, v125, v108
	v_exp_f32_e32 v191, v121
	v_sub_f32_e32 v121, v154, v108
	v_add_f32_e32 v3, 0, v110
	v_exp_f32_e32 v192, v121
	v_sub_f32_e32 v121, v155, v108
	v_add_f32_e32 v3, v109, v3
	v_exp_f32_e32 v193, v121
	v_sub_f32_e32 v121, v157, v108
	v_add_f32_e32 v3, v111, v3
	v_exp_f32_e32 v157, v121
	v_sub_f32_e32 v121, v158, v108
	v_add_f32_e32 v3, v191, v3
	v_exp_f32_e32 v158, v121
	v_sub_f32_e32 v121, v159, v108
	v_add_f32_e32 v3, v192, v3
	v_exp_f32_e32 v159, v121
	v_sub_f32_e32 v121, v160, v108
	v_add_f32_e32 v3, v193, v3
	v_exp_f32_e32 v160, v121
	v_sub_f32_e32 v121, v161, v108
	v_add_f32_e32 v3, v157, v3
	v_exp_f32_e32 v161, v121
	v_sub_f32_e32 v121, v170, v108
	v_add_f32_e32 v3, v158, v3
	v_exp_f32_e32 v198, v121
	v_sub_f32_e32 v121, v171, v108
	v_add_f32_e32 v3, v159, v3
	v_exp_f32_e32 v199, v121
	v_sub_f32_e32 v121, v172, v108
	v_add_f32_e32 v3, v160, v3
	v_exp_f32_e32 v200, v121
	v_sub_f32_e32 v121, v173, v108
	v_add_f32_e32 v3, v161, v3
	v_exp_f32_e32 v201, v121
	v_sub_f32_e32 v121, v174, v108
	v_add_f32_e32 v3, v198, v3
	v_exp_f32_e32 v202, v121
	v_sub_f32_e32 v121, v175, v108
	v_add_f32_e32 v3, v199, v3
	v_exp_f32_e32 v203, v121
	v_sub_f32_e32 v121, v176, v108
	v_add_f32_e32 v3, v200, v3
	v_exp_f32_e32 v204, v121
	v_sub_f32_e32 v121, v177, v108
	v_add_f32_e32 v3, v201, v3
	v_exp_f32_e32 v205, v121
	v_sub_f32_e32 v121, v178, v108
	v_add_f32_e32 v3, v202, v3
	v_exp_f32_e32 v206, v121
	v_sub_f32_e32 v121, v179, v108
	v_add_f32_e32 v3, v203, v3
	v_exp_f32_e32 v207, v121
	v_sub_f32_e32 v121, v180, v108
	v_add_f32_e32 v3, v204, v3
	v_exp_f32_e32 v219, v121
	v_sub_f32_e32 v121, v181, v108
	v_add_f32_e32 v3, v205, v3
	v_exp_f32_e32 v220, v121
	v_sub_f32_e32 v121, v182, v108
	v_add_f32_e32 v3, v206, v3
	v_exp_f32_e32 v221, v121
	v_sub_f32_e32 v121, v183, v108
	v_add_f32_e32 v3, v207, v3
	v_exp_f32_e32 v125, v121
	v_sub_f32_e32 v121, v184, v108
	v_add_f32_e32 v3, v219, v3
	v_exp_f32_e32 v154, v121
	v_sub_f32_e32 v121, v185, v108
	v_add_f32_e32 v3, v220, v3
	v_exp_f32_e32 v155, v121
	v_sub_f32_e32 v121, v186, v108
	v_add_f32_e32 v3, v221, v3
	v_exp_f32_e32 v222, v121
	v_sub_f32_e32 v121, v187, v108
	v_add_f32_e32 v3, v125, v3
	v_exp_f32_e32 v223, v121
	v_sub_f32_e32 v121, v188, v108
	v_add_f32_e32 v3, v154, v3
	v_exp_f32_e32 v224, v121
	v_sub_f32_e32 v121, v189, v108
	v_add_f32_e32 v3, v155, v3
	v_exp_f32_e32 v225, v121
	v_sub_f32_e32 v121, v190, v108
	v_add_f32_e32 v3, v222, v3
	v_exp_f32_e32 v226, v121
	v_sub_f32_e32 v104, v104, v108
	v_add_f32_e32 v3, v223, v3
	v_exp_f32_e32 v104, v104
	v_sub_f32_e32 v105, v105, v108
	v_add_f32_e32 v3, v224, v3
	v_exp_f32_e32 v105, v105
	v_sub_f32_e32 v106, v106, v108
	v_add_f32_e32 v3, v225, v3
	v_exp_f32_e32 v106, v106
	v_sub_f32_e32 v107, v107, v108
	v_add_f32_e32 v3, v226, v3
	v_exp_f32_e32 v107, v107
	v_add_f32_e32 v3, v104, v3
	v_add_f32_e32 v3, v105, v3
	v_add_f32_e32 v3, v106, v3
	v_add_f32_e32 v3, v107, v3
	ds_bpermute_b32 v121, v141, v3
	v_fma_f32 v1, v1, s65, -v108
	v_lshlrev_b32_e32 v108, 1, v0
	v_and_b32_e32 v174, 3, v0
	v_cvt_pk_bf16_f32 v0, v104, v105
	v_and_or_b32 v104, v108, s67, v174
	v_mul_lo_u32 v104, v104, s94
	v_cvt_pk_bf16_f32 v173, v157, v158
	v_and_b32_e32 v157, 24, v108
	v_xor_b32_e32 v157, v130, v157
	v_add3_u32 v157, v143, v157, v104
	v_add_u32_e32 v158, 0x9000, v157
	s_waitcnt lgkmcnt(0)
	v_add_f32_e32 v3, v3, v121
	v_exp_f32_e32 v121, v1
	v_cvt_pk_bf16_f32 v1, v106, v107
	ds_read2_b64 v[104:107], v158 offset1:4
	v_cvt_pk_bf16_f32 v170, v110, v109
	v_cvt_pk_bf16_f32 v171, v111, v191
	v_cvt_pk_bf16_f32 v172, v192, v193
	v_add_u32_e32 v227, 0x9800, v157
	ds_read2_b64 v[178:181], v227 offset0:20 offset1:24
	s_waitcnt lgkmcnt(1)
	v_mfma_f32_16x16x32_bf16 v[174:177], v[104:107], v[170:173], 0
	v_add_u32_e32 v104, 0x9100, v157
	ds_read2_b64 v[108:111], v104 offset1:240
	s_waitcnt lgkmcnt(1)
	v_mov_b32_e32 v106, v178
	v_mov_b32_e32 v107, v179
	v_mov_b32_e32 v178, v180
	v_mov_b32_e32 v179, v181
	s_waitcnt lgkmcnt(0)
	v_mov_b32_e32 v104, v110
	v_mov_b32_e32 v105, v111
	v_add_u32_e32 v110, 0xd000, v157
	v_add_u32_e32 v111, 0xd800, v157
	v_mfma_f32_16x16x32_bf16 v[182:185], v[104:107], v[170:173], 0
	ds_read2_b64 v[104:107], v110 offset0:128 offset1:132
	ds_read2_b64 v[190:193], v111 offset0:148 offset1:152
	ds_bpermute_b32 v123, v142, v3
	s_waitcnt lgkmcnt(2)
	v_mfma_f32_16x16x32_bf16 v[186:189], v[104:107], v[170:173], 0
	v_add_u32_e32 v104, 0xd500, v157
	ds_read2_b64 v[104:107], v104 offset1:240
	s_waitcnt lgkmcnt(2)
	v_mov_b32_e32 v196, v190
	v_mov_b32_e32 v197, v191
	v_mov_b32_e32 v190, v192
	v_mov_b32_e32 v191, v193
	s_waitcnt lgkmcnt(0)
	v_mov_b32_e32 v194, v106
	v_mov_b32_e32 v195, v107
	v_mov_b32_e32 v106, v104
	v_mov_b32_e32 v107, v105
	v_mfma_f32_16x16x32_bf16 v[170:173], v[194:197], v[170:173], 0
	v_cvt_pk_bf16_f32 v195, v161, v198
	v_cvt_pk_bf16_f32 v196, v199, v200
	v_cvt_pk_bf16_f32 v197, v201, v202
	ds_read2_b64 v[198:201], v158 offset0:8 offset1:12
	v_cvt_pk_bf16_f32 v194, v159, v160
	v_add_f32_e32 v123, v3, v123
	v_mov_b32_e32 v3, v2
	s_waitcnt lgkmcnt(0)
	v_mfma_f32_16x16x32_bf16 v[174:177], v[198:201], v[194:197], v[174:177]
	ds_read2_b64 v[198:201], v227 offset0:28 offset1:32
	v_lshl_add_u64 v[130:131], v[130:131], 1, v[132:133]
	s_waitcnt lgkmcnt(0)
	v_mov_b32_e32 v180, v198
	v_mov_b32_e32 v181, v199
	v_mov_b32_e32 v198, v200
	v_mov_b32_e32 v199, v201
	v_mfma_f32_16x16x32_bf16 v[178:181], v[178:181], v[194:197], v[182:185]
	s_nop 2
	ds_read2_b64 v[182:185], v110 offset0:136 offset1:140
	s_waitcnt lgkmcnt(0)
	v_mfma_f32_16x16x32_bf16 v[182:185], v[182:185], v[194:197], v[186:189]
	s_nop 2
	ds_read2_b64 v[186:189], v111 offset0:156 offset1:160
	s_waitcnt lgkmcnt(0)
	v_mov_b32_e32 v192, v186
	v_mov_b32_e32 v193, v187
	v_mov_b32_e32 v186, v188
	v_mov_b32_e32 v187, v189
	v_mfma_f32_16x16x32_bf16 v[170:173], v[190:193], v[194:197], v[170:173]
	ds_read2_b64 v[194:197], v158 offset0:16 offset1:20
	v_cvt_pk_bf16_f32 v190, v203, v204
	v_cvt_pk_bf16_f32 v191, v205, v206
	v_cvt_pk_bf16_f32 v192, v207, v219
	v_cvt_pk_bf16_f32 v193, v220, v221
	s_waitcnt lgkmcnt(0)
	s_nop 0
	v_mfma_f32_16x16x32_bf16 v[174:177], v[194:197], v[190:193], v[174:177]
	ds_read2_b64 v[194:197], v227 offset0:36 offset1:40
	s_waitcnt lgkmcnt(0)
	v_mov_b32_e32 v200, v194
	v_mov_b32_e32 v201, v195
	v_mov_b32_e32 v194, v196
	v_mov_b32_e32 v195, v197
	v_mfma_f32_16x16x32_bf16 v[178:181], v[198:201], v[190:193], v[178:181]
	ds_read2_b64 v[198:201], v110 offset0:144 offset1:148
	s_waitcnt lgkmcnt(0)
	v_mfma_f32_16x16x32_bf16 v[182:185], v[198:201], v[190:193], v[182:185]
	ds_read2_b64 v[198:201], v111 offset0:164 offset1:168
	s_waitcnt lgkmcnt(0)
	v_mov_b32_e32 v188, v198
	v_mov_b32_e32 v189, v199
	v_mov_b32_e32 v198, v200
	v_mov_b32_e32 v199, v201
	v_mfma_f32_16x16x32_bf16 v[170:173], v[186:189], v[190:193], v[170:173]
	ds_read2_b64 v[190:193], v158 offset0:24 offset1:28
	v_cvt_pk_bf16_f32 v186, v125, v154
	v_cvt_pk_bf16_f32 v187, v155, v222
	v_cvt_pk_bf16_f32 v188, v223, v224
	v_cvt_pk_bf16_f32 v189, v225, v226
	s_waitcnt lgkmcnt(0)
	s_nop 0
	v_mfma_f32_16x16x32_bf16 v[174:177], v[190:193], v[186:189], v[174:177]
	ds_read2_b64 v[190:193], v227 offset0:44 offset1:48
	s_waitcnt lgkmcnt(0)
	v_mov_b32_e32 v196, v190
	v_mov_b32_e32 v197, v191
	v_mov_b32_e32 v190, v192
	v_mov_b32_e32 v191, v193
	v_mfma_f32_16x16x32_bf16 v[178:181], v[194:197], v[186:189], v[178:181]
	ds_read2_b64 v[194:197], v110 offset0:152 offset1:156
	v_mov_b32_e32 v110, v108
	s_waitcnt lgkmcnt(0)
	v_mfma_f32_16x16x32_bf16 v[182:185], v[194:197], v[186:189], v[182:185]
	ds_read2_b64 v[194:197], v111 offset0:172 offset1:176
	v_mov_b32_e32 v111, v109
	s_waitcnt lgkmcnt(0)
	v_mov_b32_e32 v200, v194
	v_mov_b32_e32 v201, v195
	v_mov_b32_e32 v194, v196
	v_mov_b32_e32 v195, v197
	v_mfma_f32_16x16x32_bf16 v[170:173], v[198:201], v[186:189], v[170:173]
	v_mfma_f32_16x16x32_bf16 v[108:111], v[108:111], v[0:3], v[174:177]
	v_mfma_f32_16x16x32_bf16 v[174:177], v[190:193], v[0:3], v[178:181]
	v_mfma_f32_16x16x32_bf16 v[104:107], v[104:107], v[0:3], v[182:185]
	v_mfma_f32_16x16x32_bf16 v[170:173], v[194:197], v[0:3], v[170:173]
	v_add_f32_e32 v0, v121, v123
	v_div_scale_f32 v1, s[40:41], v0, v0, 1.0
	v_rcp_f32_e32 v3, v1
	s_mov_b64 s[40:41], 0x7e00400
	v_lshl_add_u64 v[132:133], v[130:131], 0, s[40:41]
	v_fma_f32 v121, -v1, v3, 1.0
	v_fmac_f32_e32 v3, v121, v3
	v_div_scale_f32 v121, vcc, 1.0, v0, 1.0
	v_mul_f32_e32 v123, v121, v3
	v_fma_f32 v125, -v1, v123, v121
	v_fmac_f32_e32 v123, v125, v3
	v_fma_f32 v1, -v1, v123, v121
	v_div_fmas_f32 v1, v1, v3, v123
	v_div_fixup_f32 v0, v1, v0, 1.0
	v_pk_mul_f32 v[108:109], v[108:109], v[0:1] op_sel_hi:[1,0]
	v_pk_mul_f32 v[110:111], v[110:111], v[0:1] op_sel_hi:[1,0]
	v_pk_mul_f32 v[104:105], v[104:105], v[0:1] op_sel_hi:[1,0]
	v_pk_mul_f32 v[106:107], v[106:107], v[0:1] op_sel_hi:[1,0]
	v_cvt_pk_bf16_f32 v108, v108, v109
	v_cvt_pk_bf16_f32 v109, v110, v111
	v_pk_mul_f32 v[110:111], v[174:175], v[0:1] op_sel_hi:[1,0]
	v_pk_mul_f32 v[134:135], v[176:177], v[0:1] op_sel_hi:[1,0]
	v_add_co_u32_e32 v130, vcc, s74, v130
	v_cvt_pk_bf16_f32 v104, v104, v105
	v_cvt_pk_bf16_f32 v105, v106, v107
	v_pk_mul_f32 v[106:107], v[170:171], v[0:1] op_sel_hi:[1,0]
	v_pk_mul_f32 v[0:1], v[172:173], v[0:1] op_sel_hi:[1,0]
	v_cvt_pk_bf16_f32 v110, v110, v111
	v_cvt_pk_bf16_f32 v111, v134, v135
	v_addc_co_u32_e32 v131, vcc, 0, v131, vcc
	v_cvt_pk_bf16_f32 v106, v106, v107
	v_cvt_pk_bf16_f32 v107, v0, v1
	global_store_dwordx4 v[130:131], v[108:111], off offset:1024 nt
	global_store_dwordx4 v[132:133], v[104:107], off offset:64 nt
	s_cbranch_scc1 .LBB0_425
.LBB0_429:
	s_waitcnt vmcnt(3)
	v_lshlrev_b32_e32 v170, 16, v96
	v_and_b32_e32 v171, 0xffff0000, v96
	v_lshlrev_b32_e32 v158, 16, v97
	v_and_b32_e32 v159, 0xffff0000, v97
	v_pk_mul_f32 v[96:97], v[170:171], v[170:171]
	v_pk_mul_f32 v[160:161], v[158:159], v[158:159]
	v_add_f32_e32 v3, v96, v97
	v_lshlrev_b32_e32 v154, 16, v98
	v_and_b32_e32 v155, 0xffff0000, v98
	v_add_f32_e32 v3, v160, v3
	v_lshlrev_b32_e32 v132, 16, v99
	v_and_b32_e32 v133, 0xffff0000, v99
	v_pk_mul_f32 v[98:99], v[154:155], v[154:155]
	v_add_f32_e32 v3, v161, v3
	v_add_f32_e32 v3, v98, v3
	v_pk_mul_f32 v[134:135], v[132:133], v[132:133]
	v_add_f32_e32 v3, v99, v3
	s_waitcnt vmcnt(2)
	v_lshlrev_b32_e32 v130, 16, v100
	v_and_b32_e32 v131, 0xffff0000, v100
	v_add_f32_e32 v3, v134, v3
	v_lshlrev_b32_e32 v110, 16, v101
	v_and_b32_e32 v111, 0xffff0000, v101
	v_pk_mul_f32 v[100:101], v[130:131], v[130:131]
	v_add_f32_e32 v3, v135, v3
	v_add_f32_e32 v3, v100, v3
	v_pk_mul_f32 v[106:107], v[110:111], v[110:111]
	v_add_f32_e32 v3, v101, v3
	v_lshlrev_b32_e32 v108, 16, v102
	v_and_b32_e32 v109, 0xffff0000, v102
	v_add_f32_e32 v3, v106, v3
	v_lshlrev_b32_e32 v0, 16, v103
	v_and_b32_e32 v1, 0xffff0000, v103
	v_pk_mul_f32 v[102:103], v[108:109], v[108:109]
	v_add_f32_e32 v3, v107, v3
	v_add_f32_e32 v3, v102, v3
	v_pk_mul_f32 v[104:105], v[0:1], v[0:1]
	v_add_f32_e32 v3, v103, v3
	v_add_f32_e32 v3, v104, v3
	v_add_f32_e32 v3, v105, v3
	ds_bpermute_b32 v96, v141, v3
	s_add_u32 s72, s12, s70
	s_addc_u32 s73, s13, s71
	s_add_i32 s40, s9, -1
	s_waitcnt lgkmcnt(0)
	v_add_f32_e32 v3, v3, v96
	ds_bpermute_b32 v96, v142, v3
	s_waitcnt lgkmcnt(0)
	v_add_f32_e32 v3, v3, v96
	v_fmamk_f32 v3, v3, 0x3c800000, v209
	v_mul_f32_e32 v96, 0x4b800000, v3
	v_cmp_gt_f32_e32 vcc, s68, v3
	s_nop 1
	v_cndmask_b32_e32 v3, v3, v96, vcc
	v_rsq_f32_e32 v3, v3
	s_nop 0
	v_mul_f32_e32 v96, 0x45800000, v3
	v_cndmask_b32_e32 v3, v3, v96, vcc
	v_mul_f32_e32 v100, 0x3e38aa3b, v3
	v_pk_mul_f32 v[96:97], v[100:101], v[170:171] op_sel_hi:[0,1]
	s_waitcnt vmcnt(4)
	v_pk_mul_f32 v[96:97], v[4:5], v[96:97]
	v_pk_mul_f32 v[0:1], v[100:101], v[0:1] op_sel_hi:[0,1]
	v_cvt_pk_bf16_f32 v102, v96, v97
	v_pk_mul_f32 v[96:97], v[100:101], v[158:159] op_sel_hi:[0,1]
	v_pk_mul_f32 v[96:97], v[6:7], v[96:97]
	s_waitcnt vmcnt(1)
	v_pk_mul_f32 v[0:1], v[18:19], v[0:1]
	v_cvt_pk_bf16_f32 v103, v96, v97
	v_pk_mul_f32 v[96:97], v[100:101], v[154:155] op_sel_hi:[0,1]
	v_pk_mul_f32 v[96:97], v[8:9], v[96:97]
	v_mov_b32_e32 v3, v113
	v_cvt_pk_bf16_f32 v104, v96, v97
	v_pk_mul_f32 v[96:97], v[100:101], v[132:133] op_sel_hi:[0,1]
	v_pk_mul_f32 v[96:97], v[10:11], v[96:97]
	s_nop 0
	v_cvt_pk_bf16_f32 v105, v96, v97
	v_pk_mul_f32 v[96:97], v[100:101], v[130:131] op_sel_hi:[0,1]
	v_pk_mul_f32 v[96:97], v[12:13], v[96:97]
	v_mfma_f32_16x16x32_bf16 v[194:197], v[80:83], v[102:105], 0
	v_cvt_pk_bf16_f32 v106, v96, v97
	v_pk_mul_f32 v[96:97], v[100:101], v[110:111] op_sel_hi:[0,1]
	v_pk_mul_f32 v[96:97], v[14:15], v[96:97]
	s_nop 0
	v_cvt_pk_bf16_f32 v107, v96, v97
	v_pk_mul_f32 v[96:97], v[100:101], v[108:109] op_sel_hi:[0,1]
	v_pk_mul_f32 v[96:97], v[16:17], v[96:97]
	v_cvt_pk_bf16_f32 v109, v0, v1
	v_cvt_pk_bf16_f32 v108, v96, v97
	v_mfma_f32_16x16x32_bf16 v[96:99], v[24:27], v[102:105], 0
	v_mov_b32_e32 v100, v112
	v_mfma_f32_16x16x32_bf16 v[130:133], v[28:31], v[106:109], v[96:99]
	v_lshlrev_b32_e32 v0, 3, v3
	v_ashrrev_i32_e32 v1, 31, v0
	v_ashrrev_i32_e32 v101, 31, v100
	v_mfma_f32_16x16x32_bf16 v[96:99], v[32:35], v[102:105], 0
	v_lshlrev_b32_e32 v3, 2, v3
	v_sub_u32_e32 v3, v100, v3
	v_cmp_gt_i32_e64 s[48:49], 0, v3
	v_mfma_f32_16x16x32_bf16 v[170:173], v[36:39], v[106:109], v[96:99]
	v_cmp_gt_i32_e64 s[50:51], 1, v3
	v_cmp_gt_i32_e64 s[52:53], 2, v3
	v_cmp_gt_i32_e64 s[54:55], 3, v3
	v_mfma_f32_16x16x32_bf16 v[96:99], v[40:43], v[102:105], 0
	v_cmp_lt_i32_e64 s[44:45], -1, v3
	v_cmp_lt_i32_e64 s[42:43], 0, v3
	v_mfma_f32_16x16x32_bf16 v[174:177], v[44:47], v[106:109], v[96:99]
	v_mfma_f32_16x16x32_bf16 v[96:99], v[48:51], v[102:105], 0
	v_mfma_f32_16x16x32_bf16 v[178:181], v[52:55], v[106:109], v[96:99]
	v_mfma_f32_16x16x32_bf16 v[96:99], v[56:59], v[102:105], 0
	v_mfma_f32_16x16x32_bf16 v[182:185], v[60:63], v[106:109], v[96:99]
	v_mfma_f32_16x16x32_bf16 v[96:99], v[64:67], v[102:105], 0
	v_mfma_f32_16x16x32_bf16 v[186:189], v[68:71], v[106:109], v[96:99]
	v_mfma_f32_16x16x32_bf16 v[96:99], v[72:75], v[102:105], 0
	v_mfma_f32_16x16x32_bf16 v[190:193], v[76:79], v[106:109], v[96:99]
	v_mfma_f32_16x16x32_bf16 v[102:105], v[88:91], v[102:105], 0
	s_nop 5
	v_lshlrev_b64 v[98:99], 1, v[0:1]
	v_cvt_f32_u32_e32 v1, s40
	v_lshl_add_u64 v[96:97], v[126:127], 0, v[100:101]
	v_mad_u64_u32 v[110:111], s[40:41], v96, s62, v[98:99]
	v_cmp_lt_f32_e32 vcc, s57, v1
	s_and_b64 s[40:41], vcc, exec
	s_cselect_b32 s40, 0xffffffc0, 0
	v_cndmask_b32_e32 v101, 0, v215, vcc
	v_sub_f32_e32 v1, v101, v1
	v_exp_f32_e32 v1, v1
	v_cmp_lt_i32_e32 vcc, 2, v3
	s_cmp_eq_u32 s70, 0
	v_mfma_f32_16x16x32_bf16 v[194:197], v[84:87], v[106:109], v[194:197]
	v_ldexp_f32 v1, v1, s40
	v_cmp_lt_i32_e64 s[40:41], 1, v3
	v_add_u32_e32 v3, 0x80, v3
	v_cvt_f32_i32_e32 v157, v3
	v_mfma_f32_16x16x32_bf16 v[102:105], v[92:95], v[106:109], v[102:105]
	v_mul_f32_e32 v106, 0x3fb8aa3b, v1
	s_cselect_b64 s[46:47], -1, 0
	s_cmp_eq_u32 s14, 2
	s_cselect_b64 s[56:57], -1, 0
	v_pk_mul_f32 v[108:109], v[106:107], v[156:157] op_sel_hi:[0,1]
	s_waitcnt vmcnt(0)
	v_cndmask_b32_e64 v3, v23, v22, s[56:57]
	v_fma_f32 v107, v106, 0, -v109
	v_cndmask_b32_e64 v101, v3, v20, s[46:47]
	v_add_f32_e32 v107, v107, v130
	s_and_b64 s[46:47], s[78:79], s[48:49]
	v_fma_f32 v1, v1, s65, -v109
	v_cndmask_b32_e64 v121, v216, v107, s[46:47]
	v_add_f32_e32 v1, v1, v131
	s_and_b64 s[46:47], s[78:79], s[50:51]
	v_fma_f32 v107, v106, 2.0, -v109
	v_cndmask_b32_e64 v1, v216, v1, s[46:47]
	v_add_f32_e32 v107, v107, v132
	s_and_b64 s[46:47], s[78:79], s[52:53]
	v_cndmask_b32_e64 v123, v216, v107, s[46:47]
	v_fma_f32 v107, v106, s17, -v109
	v_add_f32_e32 v107, v107, v133
	s_and_b64 s[46:47], s[78:79], s[54:55]
	v_cndmask_b32_e64 v125, v216, v107, s[46:47]
	v_fma_f32 v107, v106, s18, -v109
	v_add_f32_e32 v107, v107, v170
	v_cndmask_b32_e64 v130, v216, v107, s[24:25]
	v_fma_f32 v107, v106, s19, -v109
	v_add_f32_e32 v107, v107, v171
	v_cndmask_b32_e64 v131, v216, v107, s[24:25]
	v_fma_f32 v107, v106, s20, -v109
	v_add_f32_e32 v107, v107, v172
	v_cndmask_b32_e64 v132, v216, v107, s[24:25]
	v_fma_f32 v107, v106, s21, -v109
	v_add_f32_e32 v107, v107, v173
	v_cndmask_b32_e64 v133, v216, v107, s[24:25]
	v_fma_f32 v107, v106, s22, -v109
	v_add_f32_e32 v107, v107, v174
	v_cndmask_b32_e64 v135, v216, v107, s[26:27]
	v_fma_f32 v107, v106, s0, -v109
	v_add_f32_e32 v107, v107, v175
	v_cndmask_b32_e64 v154, v216, v107, s[26:27]
	v_fma_f32 v107, v106, s33, -v109
	v_add_f32_e32 v107, v107, v176
	v_cndmask_b32_e64 v155, v216, v107, s[26:27]
	v_fma_f32 v107, v106, s61, -v109
	v_add_f32_e32 v107, v107, v177
	v_cndmask_b32_e64 v157, v216, v107, s[26:27]
	v_fma_f32 v107, v106, s4, -v109
	v_add_f32_e32 v107, v107, v178
	v_cndmask_b32_e64 v158, v216, v107, s[28:29]
	v_fma_f32 v107, v106, s81, -v109
	v_add_f32_e32 v107, v107, v179
	v_cndmask_b32_e64 v159, v216, v107, s[28:29]
	v_fma_f32 v107, v106, s69, -v109
	v_add_f32_e32 v107, v107, v180
	v_cndmask_b32_e64 v160, v216, v107, s[28:29]
	v_fma_f32 v107, v106, s59, -v109
	v_add_f32_e32 v107, v107, v181
	v_cndmask_b32_e64 v161, v216, v107, s[28:29]
	v_fma_f32 v107, v106, s16, -v109
	v_add_f32_e32 v107, v107, v182
	v_cndmask_b32_e64 v170, v216, v107, s[30:31]
	v_fma_f32 v107, v106, s58, -v109
	v_add_f32_e32 v107, v107, v183
	v_cndmask_b32_e64 v171, v216, v107, s[30:31]
	v_fma_f32 v107, v106, s64, -v109
	v_add_f32_e32 v107, v107, v184
	v_cndmask_b32_e64 v172, v216, v107, s[30:31]
	v_fma_f32 v107, v106, s3, -v109
	v_add_f32_e32 v107, v107, v185
	v_cndmask_b32_e64 v173, v216, v107, s[30:31]
	v_fma_f32 v107, v106, s2, -v109
	v_add_f32_e32 v107, v107, v186
	v_cndmask_b32_e64 v174, v216, v107, s[34:35]
	v_fma_f32 v107, v106, s63, -v109
	v_add_f32_e32 v107, v107, v187
	v_cndmask_b32_e64 v175, v216, v107, s[34:35]
	v_fma_f32 v107, v106, s82, -v109
	v_add_f32_e32 v107, v107, v188
	v_cndmask_b32_e64 v176, v216, v107, s[34:35]
	v_fma_f32 v107, v106, s83, -v109
	v_add_f32_e32 v107, v107, v189
	v_cndmask_b32_e64 v177, v216, v107, s[34:35]
	v_fma_f32 v107, v106, s80, -v109
	v_add_f32_e32 v107, v107, v190
	v_cndmask_b32_e64 v178, v216, v107, s[36:37]
	v_fma_f32 v107, v106, s90, -v109
	v_add_f32_e32 v107, v107, v191
	v_cndmask_b32_e64 v179, v216, v107, s[36:37]
	v_fma_f32 v107, v106, s91, -v109
	v_add_f32_e32 v107, v107, v192
	v_cndmask_b32_e64 v180, v216, v107, s[36:37]
	v_fma_f32 v107, v106, s88, -v109
	v_mul_f32_e32 v3, 0x3fb8aa3b, v101
	v_add_f32_e32 v107, v107, v193
	v_max3_f32 v3, v3, v121, v1
	v_cndmask_b32_e64 v181, v216, v107, s[36:37]
	v_fma_f32 v107, v106, s89, -v109
	v_max3_f32 v3, v3, v123, v125
	v_add_f32_e32 v107, v107, v194
	v_max3_f32 v3, v3, v130, v131
	v_cndmask_b32_e64 v182, v216, v107, s[38:39]
	v_fma_f32 v107, v106, s75, -v109
	v_max3_f32 v3, v3, v132, v133
	v_add_f32_e32 v107, v107, v195
	v_max3_f32 v3, v3, v135, v154
	v_cndmask_b32_e64 v183, v216, v107, s[38:39]
	v_fma_f32 v107, v106, s96, -v109
	v_max3_f32 v3, v3, v155, v157
	v_add_f32_e32 v107, v107, v196
	v_max3_f32 v3, v3, v158, v159
	v_cndmask_b32_e64 v184, v216, v107, s[38:39]
	v_fma_f32 v107, v106, s97, -v109
	v_max3_f32 v3, v3, v160, v161
	v_add_f32_e32 v107, v107, v197
	v_max3_f32 v3, v3, v170, v171
	v_cndmask_b32_e64 v185, v216, v107, s[38:39]
	v_fma_f32 v107, v106, s5, -v109
	v_max3_f32 v3, v3, v172, v173
	v_add_f32_e32 v102, v107, v102
	s_and_b64 s[44:45], s[84:85], s[44:45]
	v_max3_f32 v3, v3, v174, v175
	v_cndmask_b32_e64 v186, v216, v102, s[44:45]
	v_fma_f32 v102, v106, s60, -v109
	v_max3_f32 v3, v3, v176, v177
	v_add_f32_e32 v102, v102, v103
	s_and_b64 s[42:43], s[84:85], s[42:43]
	v_max3_f32 v3, v3, v178, v179
	v_cndmask_b32_e64 v198, v216, v102, s[42:43]
	v_fma_f32 v102, v106, s66, -v109
	v_max3_f32 v3, v3, v180, v181
	v_add_f32_e32 v102, v102, v104
	s_and_b64 s[40:41], s[84:85], s[40:41]
	v_max3_f32 v3, v3, v182, v183
	v_cndmask_b32_e64 v206, v216, v102, s[40:41]
	v_sub_f32_e32 v102, v108, v109
	v_max3_f32 v3, v3, v184, v185
	v_add_f32_e32 v102, v102, v105
	s_and_b64 vcc, s[84:85], vcc
	v_max3_f32 v3, v3, v186, v198
	v_cndmask_b32_e32 v207, v216, v102, vcc
	v_max3_f32 v3, v3, v206, v207
	ds_bpermute_b32 v104, v141, v3
	v_mov_b32_e32 v134, v111
	v_mad_u64_u32 v[102:103], s[40:41], v97, s62, v[134:135]
	v_mov_b32_e32 v111, v102
	s_waitcnt lgkmcnt(0)
	v_max_f32_e32 v104, v104, v104
	v_max_f32_e32 v3, v3, v104
	ds_bpermute_b32 v134, v142, v3
	v_lshl_add_u64 v[102:103], s[72:73], 0, v[110:111]
	s_mov_b32 s40, 0xbe00000
	v_add_co_u32_e32 v102, vcc, s40, v102
	v_lshlrev_b64 v[96:97], 11, v[96:97]
	s_nop 0
	v_addc_co_u32_e32 v103, vcc, 0, v103, vcc
	global_load_dwordx4 v[104:107], v[102:103], off offset:3200
	global_load_dwordx4 v[108:111], v[102:103], off offset:3264
	s_waitcnt lgkmcnt(0)
	v_max_f32_e32 v102, v134, v134
	v_max_f32_e32 v102, v3, v102
	v_sub_f32_e32 v3, v121, v102
	v_sub_f32_e32 v121, v125, v102
	v_sub_f32_e32 v125, v130, v102
	v_sub_f32_e32 v130, v131, v102
	v_exp_f32_e32 v134, v130
	v_sub_f32_e32 v130, v132, v102
	v_exp_f32_e32 v187, v130
	v_sub_f32_e32 v130, v133, v102
	v_exp_f32_e32 v188, v130
	v_sub_f32_e32 v130, v135, v102
	v_exp_f32_e32 v135, v130
	v_sub_f32_e32 v130, v154, v102
	v_exp_f32_e32 v154, v130
	v_sub_f32_e32 v130, v155, v102
	v_exp_f32_e32 v155, v130
	v_sub_f32_e32 v130, v157, v102
	v_exp_f32_e32 v157, v130
	v_sub_f32_e32 v130, v158, v102
	v_exp_f32_e32 v158, v130
	v_sub_f32_e32 v130, v159, v102
	v_exp_f32_e32 v159, v130
	v_sub_f32_e32 v130, v160, v102
	v_exp_f32_e32 v160, v130
	v_sub_f32_e32 v130, v161, v102
	v_exp_f32_e32 v161, v130
	v_sub_f32_e32 v130, v170, v102
	v_exp_f32_e32 v219, v130
	v_sub_f32_e32 v130, v171, v102
	v_exp_f32_e32 v224, v130
	v_sub_f32_e32 v130, v172, v102
	v_exp_f32_e32 v225, v130
	v_sub_f32_e32 v130, v173, v102
	v_exp_f32_e32 v226, v130
	v_sub_f32_e32 v130, v174, v102
	v_exp_f32_e32 v227, v130
	v_sub_f32_e32 v130, v175, v102
	v_exp_f32_e32 v228, v130
	v_sub_f32_e32 v130, v176, v102
	v_exp_f32_e32 v229, v130
	v_sub_f32_e32 v130, v177, v102
	v_exp_f32_e32 v230, v130
	v_sub_f32_e32 v130, v178, v102
	v_exp_f32_e32 v231, v130
	v_sub_f32_e32 v130, v179, v102
	v_exp_f32_e32 v232, v130
	v_sub_f32_e32 v130, v180, v102
	v_exp_f32_e32 v233, v130
	v_sub_f32_e32 v130, v181, v102
	v_exp_f32_e32 v234, v130
	v_sub_f32_e32 v130, v182, v102
	v_exp_f32_e32 v235, v130
	v_sub_f32_e32 v130, v183, v102
	v_exp_f32_e32 v3, v3
	v_sub_f32_e32 v1, v1, v102
	v_exp_f32_e32 v236, v130
	v_sub_f32_e32 v130, v184, v102
	v_exp_f32_e32 v1, v1
	v_sub_f32_e32 v103, v123, v102
	v_exp_f32_e32 v237, v130
	v_sub_f32_e32 v130, v185, v102
	v_exp_f32_e32 v103, v103
	v_exp_f32_e32 v238, v130
	v_sub_f32_e32 v130, v186, v102
	v_exp_f32_e32 v121, v121
	v_exp_f32_e32 v239, v130
	v_lshlrev_b32_e32 v130, 1, v100
	v_and_b32_e32 v100, 3, v100
	v_add_f32_e32 v123, 0, v3
	v_exp_f32_e32 v125, v125
	v_and_or_b32 v100, v130, s67, v100
	v_add_f32_e32 v123, v1, v123
	v_mul_lo_u32 v100, v100, s94
	v_add_f32_e32 v123, v103, v123
	v_and_b32_e32 v130, 24, v130
	v_xor_b32_e32 v0, v0, v130
	v_add3_u32 v0, v143, v0, v100
	v_add_f32_e32 v123, v121, v123
	v_add_u32_e32 v100, 0x9000, v0
	v_add_f32_e32 v123, v125, v123
	ds_read2_b64 v[130:133], v100 offset1:4
	v_add_f32_e32 v123, v134, v123
	v_cvt_pk_bf16_f32 v170, v3, v1
	v_add_u32_e32 v1, 0x9100, v0
	v_add_f32_e32 v123, v187, v123
	v_cvt_pk_bf16_f32 v171, v103, v121
	ds_read2_b64 v[174:177], v1 offset1:240
	v_add_u32_e32 v1, 0x9800, v0
	v_add_u32_e32 v3, 0xd000, v0
	v_add_u32_e32 v103, 0xd500, v0
	v_add_u32_e32 v0, 0xd800, v0
	v_add_f32_e32 v123, v188, v123
	ds_read2_b64 v[178:181], v1 offset0:20 offset1:24
	v_cvt_pk_bf16_f32 v173, v187, v188
	ds_read2_b64 v[182:185], v3 offset0:128 offset1:132
	ds_read2_b64 v[186:189], v103 offset1:240
	ds_read2_b64 v[190:193], v0 offset0:148 offset1:152
	ds_read2_b64 v[194:197], v100 offset0:8 offset1:12
	v_cvt_pk_bf16_f32 v172, v125, v134
	v_sub_f32_e32 v121, v198, v102
	ds_read2_b64 v[198:201], v1 offset0:28 offset1:32
	s_waitcnt lgkmcnt(7)
	v_mfma_f32_16x16x32_bf16 v[130:133], v[130:133], v[170:173], 0
	v_add_f32_e32 v123, v135, v123
	v_add_f32_e32 v123, v154, v123
	v_add_f32_e32 v123, v155, v123
	s_waitcnt lgkmcnt(5)
	v_mfma_f32_16x16x32_bf16 v[176:179], v[176:179], v[170:173], 0
	v_add_f32_e32 v123, v157, v123
	v_add_f32_e32 v123, v158, v123
	v_add_f32_e32 v123, v159, v123
	s_waitcnt lgkmcnt(4)
	v_mfma_f32_16x16x32_bf16 v[182:185], v[182:185], v[170:173], 0
	v_add_f32_e32 v123, v160, v123
	ds_read2_b64 v[220:223], v0 offset0:156 offset1:160
	v_add_f32_e32 v123, v161, v123
	s_waitcnt lgkmcnt(3)
	v_mfma_f32_16x16x32_bf16 v[170:173], v[188:191], v[170:173], 0
	v_cvt_pk_bf16_f32 v188, v135, v154
	v_cvt_pk_bf16_f32 v189, v155, v157
	v_cvt_pk_bf16_f32 v190, v158, v159
	v_cvt_pk_bf16_f32 v191, v160, v161
	ds_read2_b64 v[202:205], v3 offset0:136 offset1:140
	v_add_f32_e32 v123, v219, v123
	s_waitcnt lgkmcnt(3)
	v_mfma_f32_16x16x32_bf16 v[130:133], v[194:197], v[188:191], v[130:133]
	v_mov_b32_e32 v194, v180
	v_mov_b32_e32 v195, v181
	s_waitcnt lgkmcnt(2)
	v_mov_b32_e32 v196, v198
	v_mov_b32_e32 v197, v199
	v_add_f32_e32 v123, v224, v123
	v_add_f32_e32 v123, v225, v123
	v_mfma_f32_16x16x32_bf16 v[176:179], v[194:197], v[188:191], v[176:179]
	ds_read2_b64 v[196:199], v100 offset0:16 offset1:20
	v_add_f32_e32 v123, v226, v123
	s_waitcnt lgkmcnt(2)
	v_mov_b32_e32 v194, v220
	v_mov_b32_e32 v195, v221
	v_add_f32_e32 v123, v227, v123
	v_add_f32_e32 v123, v228, v123
	v_add_f32_e32 v123, v229, v123
	v_add_f32_e32 v123, v230, v123
	v_add_f32_e32 v123, v231, v123
	s_waitcnt lgkmcnt(1)
	v_mfma_f32_16x16x32_bf16 v[180:183], v[202:205], v[188:191], v[182:185]
	v_add_f32_e32 v123, v232, v123
	v_add_f32_e32 v123, v233, v123
	v_add_f32_e32 v123, v234, v123
	v_mfma_f32_16x16x32_bf16 v[170:173], v[192:195], v[188:191], v[170:173]
	v_cvt_pk_bf16_f32 v188, v219, v224
	v_cvt_pk_bf16_f32 v189, v225, v226
	v_cvt_pk_bf16_f32 v190, v227, v228
	v_cvt_pk_bf16_f32 v191, v229, v230
	ds_read2_b64 v[192:195], v1 offset0:36 offset1:40
	v_add_f32_e32 v123, v235, v123
	s_waitcnt lgkmcnt(1)
	v_mfma_f32_16x16x32_bf16 v[130:133], v[196:199], v[188:191], v[130:133]
	v_mov_b32_e32 v196, v200
	v_mov_b32_e32 v197, v201
	ds_read2_b64 v[200:203], v3 offset0:144 offset1:148
	v_add_f32_e32 v123, v236, v123
	v_add_f32_e32 v123, v237, v123
	v_add_f32_e32 v123, v238, v123
	v_add_f32_e32 v103, v239, v123
	v_exp_f32_e32 v121, v121
	v_sub_f32_e32 v123, v206, v102
	s_waitcnt lgkmcnt(1)
	v_mov_b32_e32 v198, v192
	v_mov_b32_e32 v199, v193
	v_sub_f32_e32 v125, v207, v102
	ds_read2_b64 v[204:207], v0 offset0:164 offset1:168
	v_exp_f32_e32 v123, v123
	v_exp_f32_e32 v125, v125
	s_waitcnt lgkmcnt(1)
	v_mfma_f32_16x16x32_bf16 v[180:183], v[200:203], v[188:191], v[180:183]
	ds_read2_b64 v[200:203], v100 offset0:24 offset1:28
	v_add_f32_e32 v103, v121, v103
	v_add_f32_e32 v103, v123, v103
	v_mfma_f32_16x16x32_bf16 v[176:179], v[196:199], v[188:191], v[176:179]
	v_mov_b32_e32 v196, v222
	v_mov_b32_e32 v197, v223
	s_waitcnt lgkmcnt(1)
	v_mov_b32_e32 v198, v204
	v_mov_b32_e32 v199, v205
	v_add_f32_e32 v100, v125, v103
	ds_bpermute_b32 v103, v141, v100
	v_mfma_f32_16x16x32_bf16 v[170:173], v[196:199], v[188:191], v[170:173]
	v_cvt_pk_bf16_f32 v188, v231, v232
	v_cvt_pk_bf16_f32 v189, v233, v234
	v_cvt_pk_bf16_f32 v190, v235, v236
	ds_read2_b64 v[196:199], v1 offset0:44 offset1:48
	v_cvt_pk_bf16_f32 v191, v237, v238
	ds_read2_b64 v[220:223], v0 offset0:172 offset1:176
	s_waitcnt lgkmcnt(2)
	v_add_f32_e32 v100, v100, v103
	v_mfma_f32_16x16x32_bf16 v[130:133], v[200:203], v[188:191], v[130:133]
	ds_read2_b64 v[200:203], v3 offset0:152 offset1:156
	ds_bpermute_b32 v103, v142, v100
	v_fma_f32 v101, v101, s65, -v102
	v_mov_b32_e32 v192, v194
	v_mov_b32_e32 v193, v195
	s_waitcnt lgkmcnt(3)
	v_mov_b32_e32 v194, v196
	v_mov_b32_e32 v195, v197
	v_cvt_pk_bf16_f32 v0, v239, v121
	v_mov_b32_e32 v204, v206
	v_mov_b32_e32 v205, v207
	s_waitcnt lgkmcnt(2)
	v_mov_b32_e32 v206, v220
	v_mov_b32_e32 v207, v221
	v_exp_f32_e32 v121, v101
	v_cvt_pk_bf16_f32 v1, v123, v125
	s_waitcnt lgkmcnt(0)
	v_add_f32_e32 v123, v100, v103
	v_mfma_f32_16x16x32_bf16 v[192:195], v[192:195], v[188:191], v[176:179]
	v_add_f32_e32 v121, v121, v123
	v_mov_b32_e32 v196, v198
	v_mov_b32_e32 v197, v199
	v_mfma_f32_16x16x32_bf16 v[178:181], v[200:203], v[188:191], v[180:183]
	v_mov_b32_e32 v176, v174
	v_mov_b32_e32 v177, v175
	v_mov_b32_e32 v220, v222
	v_mfma_f32_16x16x32_bf16 v[170:173], v[204:207], v[188:191], v[170:173]
	v_mov_b32_e32 v188, v186
	v_mov_b32_e32 v189, v187
	v_mov_b32_e32 v221, v223
	v_div_scale_f32 v123, s[40:41], v121, v121, 1.0
	v_rcp_f32_e32 v125, v123
	v_mov_b32_e32 v3, v2
	v_lshl_add_u64 v[96:97], v[96:97], 0, v[98:99]
	v_lshl_add_u64 v[134:135], s[72:73], 0, v[96:97]
	v_mfma_f32_16x16x32_bf16 v[130:133], v[174:177], v[0:3], v[130:133]
	s_or_b32 s42, s14, 1
	s_cmp_lg_u32 s14, 2
	v_mfma_f32_16x16x32_bf16 v[174:177], v[196:199], v[0:3], v[192:195]
	v_mfma_f32_16x16x32_bf16 v[100:103], v[186:189], v[0:3], v[178:181]
	v_mfma_f32_16x16x32_bf16 v[170:173], v[220:223], v[0:3], v[170:173]
	v_fma_f32 v0, -v123, v125, 1.0
	v_fmac_f32_e32 v125, v0, v125
	v_div_scale_f32 v0, vcc, 1.0, v121, 1.0
	v_mul_f32_e32 v1, v0, v125
	v_fma_f32 v3, -v123, v1, v0
	v_fmac_f32_e32 v1, v3, v125
	v_fma_f32 v0, -v123, v1, v0
	v_div_fmas_f32 v0, v0, v125, v1
	v_div_fixup_f32 v0, v0, v121, 1.0
	v_pk_mul_f32 v[96:97], v[130:131], v[0:1] op_sel_hi:[1,0]
	v_pk_mul_f32 v[98:99], v[132:133], v[0:1] op_sel_hi:[1,0]
	v_cvt_pk_bf16_f32 v96, v96, v97
	v_cvt_pk_bf16_f32 v97, v98, v99
	v_pk_mul_f32 v[98:99], v[174:175], v[0:1] op_sel_hi:[1,0]
	v_pk_mul_f32 v[130:131], v[176:177], v[0:1] op_sel_hi:[1,0]
	v_cvt_pk_bf16_f32 v98, v98, v99
	v_cvt_pk_bf16_f32 v99, v130, v131
	v_add_co_u32_e32 v130, vcc, s74, v134
	v_mov_b32_e32 v3, v113
	s_nop 0
	v_addc_co_u32_e32 v131, vcc, 0, v135, vcc
	global_store_dwordx4 v[130:131], v[96:99], off offset:1024 nt
	s_nop 1
	v_pk_mul_f32 v[96:97], v[100:101], v[0:1] op_sel_hi:[1,0]
	v_pk_mul_f32 v[98:99], v[102:103], v[0:1] op_sel_hi:[1,0]
	v_cvt_pk_bf16_f32 v96, v96, v97
	v_cvt_pk_bf16_f32 v97, v98, v99
	v_pk_mul_f32 v[98:99], v[170:171], v[0:1] op_sel_hi:[1,0]
	v_pk_mul_f32 v[0:1], v[172:173], v[0:1] op_sel_hi:[1,0]
	v_cvt_pk_bf16_f32 v98, v98, v99
	v_cvt_pk_bf16_f32 v99, v0, v1
	v_mov_b32_e32 v0, v112
	global_store_dwordx4 v[130:131], v[96:99], off offset:1088 nt
	s_nop 0
	v_ashrrev_i32_e32 v1, 31, v0
	v_lshlrev_b32_e32 v130, 3, v3
	v_ashrrev_i32_e32 v131, 31, v130
	v_lshl_add_u64 v[132:133], v[126:127], 0, v[0:1]
	s_cbranch_scc0 .LBB0_431
	s_or_b32 s40, s42, s15
	v_lshlrev_b64 v[96:97], 1, v[130:131]
	s_lshl_b32 s94, s40, 6
	v_mad_u64_u32 v[96:97], s[40:41], v132, s62, v[96:97]
	v_mov_b32_e32 v98, v97
	v_mad_u64_u32 v[98:99], s[40:41], v133, s62, v[98:99]
	s_add_u32 s40, s12, s70
	v_mov_b32_e32 v97, v98
	s_addc_u32 s41, s13, s71
	v_lshl_add_u64 v[96:97], s[40:41], 0, v[96:97]
	v_add_co_u32_e32 v100, vcc, 0xbe00000, v96
	s_nop 1
	v_addc_co_u32_e32 v101, vcc, 0, v97, vcc
	global_load_dwordx4 v[96:99], v[100:101], off offset:3328
	s_nop 0
	global_load_dwordx4 v[100:103], v[100:101], off offset:3392
	v_mov_b64_e32 v[134:135], s[94:95]
	s_mov_b32 s57, 0x42fc0000
	s_cbranch_execnz .LBB0_428
	s_branch .LBB0_427
